# in-proj epilogue: the 8 rstd loads issued up front (7 load round trips off the serial chain); per-group vmcnt(0) kept, padded so it never directly follows a store
# baseline (speedup 1.0000x reference)
;     __device__ __forceinline__ void operator()(const f32x4 (&acc)[2][2][4][2], const Unit& u, int wr, int wc, int fr, int fq) const {
;         const int row0 = u.pm * BM + wr * 64 + fr, col0 = u.pn * BM + wc * 32 + 8 * fq;
; #pragma unroll
;         for (int ai = 0; ai < 2; ++ai)
; #pragma unroll
;             for (int m = 0; m < 4; ++m) {
;                 const int row = row0 + ai * HALF + m * 16; const float s = rs[row]; bf16_t* rowp = O + (size_t)row * ldc + col0;
; #pragma unroll
;                 for (int bj = 0; bj < 2; ++bj) { const f32x4 v0 = acc[ai][bj][m][0] * s, v1 = acc[ai][bj][m][1] * s; u32x4 w;
;                     w.x = pk2(v0[0], v0[1]); w.y = pk2(v0[2], v0[3]); w.z = pk2(v1[0], v1[1]); w.w = pk2(v1[2], v1[3]); *(u32x4*)(rowp + bj * HALF) = w; }
;             }
.LBB0_165:
	v_lshl_add_u32 v146, s51, 8, v148
	v_ashrrev_i32_e32 v147, 31, v146
	v_lshl_add_u64 v[142:143], v[146:147], 2, s[14:15]
	global_load_dword v152, v[142:143], off
	global_load_dword v196, v[142:143], off offset:64
	global_load_dword v200, v[142:143], off offset:128
	global_load_dword v204, v[142:143], off offset:192
	global_load_dword v232, v[142:143], off offset:512
	global_load_dword v234, v[142:143], off offset:576
	global_load_dword v236, v[142:143], off offset:640
	global_load_dword v238, v[142:143], off offset:704
	v_lshl_or_b32 v140, s50, 8, v150
	v_ashrrev_i32_e32 v141, 31, v140
	v_lshlrev_b64 v[144:145], 12, v[146:147]
	v_lshl_add_u64 v[154:155], s[10:11], 0, v[144:145]
	v_lshlrev_b64 v[144:145], 1, v[140:141]
	v_lshl_add_u64 v[140:141], v[154:155], 0, v[144:145]
	s_mov_b32 s19, 0x80000
	s_mov_b64 s[26:27], 0x80000
	s_mov_b32 s60, 0x2dc0000
	s_waitcnt vmcnt(0)
	v_pk_mul_f32 v[128:129], v[128:129], v[152:153] op_sel_hi:[1,0]
	v_pk_mul_f32 v[126:127], v[126:127], v[152:153] op_sel_hi:[1,0]
	v_pk_mul_f32 v[154:155], v[124:125], v[152:153] op_sel_hi:[1,0]
	v_pk_mul_f32 v[124:125], v[122:123], v[152:153] op_sel_hi:[1,0]
	v_cvt_pk_bf16_f32 v122, v126, v127
	v_cvt_pk_bf16_f32 v123, v128, v129
	v_cvt_pk_bf16_f32 v124, v124, v125
	v_cvt_pk_bf16_f32 v125, v154, v155
	global_store_dwordx4 v[140:141], v[122:125], off
	v_pk_mul_f32 v[120:121], v[120:121], v[152:153] op_sel_hi:[1,0]
	v_pk_mul_f32 v[118:119], v[118:119], v[152:153] op_sel_hi:[1,0]
	v_pk_mul_f32 v[122:123], v[116:117], v[152:153] op_sel_hi:[1,0]
	v_pk_mul_f32 v[116:117], v[114:115], v[152:153] op_sel_hi:[1,0]
	v_cvt_pk_bf16_f32 v114, v118, v119
	v_cvt_pk_bf16_f32 v115, v120, v121
	v_cvt_pk_bf16_f32 v116, v116, v117
	v_cvt_pk_bf16_f32 v117, v122, v123
	global_store_dwordx4 v[140:141], v[114:117], off offset:256
	s_nop 1
	v_or_b32_e32 v114, 16, v146
	v_ashrrev_i32_e32 v115, 31, v114
	s_nop 3
	v_lshlrev_b64 v[114:115], 12, v[114:115]
	v_lshl_add_u64 v[114:115], s[10:11], 0, v[114:115]
	v_lshl_add_u64 v[114:115], v[114:115], 0, v[144:145]
	s_waitcnt vmcnt(0)
	v_pk_mul_f32 v[112:113], v[112:113], v[196:197] op_sel_hi:[1,0]
	v_pk_mul_f32 v[110:111], v[110:111], v[196:197] op_sel_hi:[1,0]
	v_pk_mul_f32 v[118:119], v[108:109], v[196:197] op_sel_hi:[1,0]
	v_pk_mul_f32 v[108:109], v[106:107], v[196:197] op_sel_hi:[1,0]
	v_cvt_pk_bf16_f32 v106, v110, v111
	v_cvt_pk_bf16_f32 v107, v112, v113
	v_cvt_pk_bf16_f32 v108, v108, v109
	v_cvt_pk_bf16_f32 v109, v118, v119
	global_store_dwordx4 v[114:115], v[106:109], off
	v_pk_mul_f32 v[104:105], v[104:105], v[196:197] op_sel_hi:[1,0]
	v_pk_mul_f32 v[102:103], v[102:103], v[196:197] op_sel_hi:[1,0]
	v_pk_mul_f32 v[106:107], v[100:101], v[196:197] op_sel_hi:[1,0]
	v_pk_mul_f32 v[100:101], v[98:99], v[196:197] op_sel_hi:[1,0]
	v_cvt_pk_bf16_f32 v98, v102, v103
	v_cvt_pk_bf16_f32 v99, v104, v105
	v_cvt_pk_bf16_f32 v100, v100, v101
	v_cvt_pk_bf16_f32 v101, v106, v107
	global_store_dwordx4 v[114:115], v[98:101], off offset:256
	s_nop 1
	v_or_b32_e32 v98, 32, v146
	v_ashrrev_i32_e32 v99, 31, v98
	s_nop 3
	v_lshlrev_b64 v[98:99], 12, v[98:99]
	v_lshl_add_u64 v[98:99], s[10:11], 0, v[98:99]
	v_lshl_add_u64 v[98:99], v[98:99], 0, v[144:145]
	s_waitcnt vmcnt(0)
	v_pk_mul_f32 v[96:97], v[96:97], v[200:201] op_sel_hi:[1,0]
	v_pk_mul_f32 v[94:95], v[94:95], v[200:201] op_sel_hi:[1,0]
	v_pk_mul_f32 v[102:103], v[92:93], v[200:201] op_sel_hi:[1,0]
	v_pk_mul_f32 v[92:93], v[90:91], v[200:201] op_sel_hi:[1,0]
	v_cvt_pk_bf16_f32 v90, v94, v95
	v_cvt_pk_bf16_f32 v91, v96, v97
	v_cvt_pk_bf16_f32 v92, v92, v93
	v_cvt_pk_bf16_f32 v93, v102, v103
	global_store_dwordx4 v[98:99], v[90:93], off
	v_pk_mul_f32 v[88:89], v[88:89], v[200:201] op_sel_hi:[1,0]
	v_pk_mul_f32 v[86:87], v[86:87], v[200:201] op_sel_hi:[1,0]
	v_pk_mul_f32 v[90:91], v[84:85], v[200:201] op_sel_hi:[1,0]
	v_pk_mul_f32 v[84:85], v[82:83], v[200:201] op_sel_hi:[1,0]
	v_cvt_pk_bf16_f32 v82, v86, v87
	v_cvt_pk_bf16_f32 v83, v88, v89
	v_cvt_pk_bf16_f32 v84, v84, v85
	v_cvt_pk_bf16_f32 v85, v90, v91
	global_store_dwordx4 v[98:99], v[82:85], off offset:256
	s_nop 1
	v_or_b32_e32 v82, 48, v146
	v_ashrrev_i32_e32 v83, 31, v82
	s_nop 3
	v_lshlrev_b64 v[82:83], 12, v[82:83]
	v_lshl_add_u64 v[82:83], s[10:11], 0, v[82:83]
	v_lshl_add_u64 v[82:83], v[82:83], 0, v[144:145]
	s_waitcnt vmcnt(0)
	v_pk_mul_f32 v[80:81], v[80:81], v[204:205] op_sel_hi:[1,0]
	v_pk_mul_f32 v[78:79], v[78:79], v[204:205] op_sel_hi:[1,0]
	v_pk_mul_f32 v[86:87], v[76:77], v[204:205] op_sel_hi:[1,0]
	v_pk_mul_f32 v[76:77], v[74:75], v[204:205] op_sel_hi:[1,0]
	v_cvt_pk_bf16_f32 v74, v78, v79
	v_cvt_pk_bf16_f32 v75, v80, v81
	v_cvt_pk_bf16_f32 v76, v76, v77
	v_cvt_pk_bf16_f32 v77, v86, v87
	global_store_dwordx4 v[82:83], v[74:77], off
	v_pk_mul_f32 v[72:73], v[72:73], v[204:205] op_sel_hi:[1,0]
	v_pk_mul_f32 v[70:71], v[70:71], v[204:205] op_sel_hi:[1,0]
	v_pk_mul_f32 v[74:75], v[68:69], v[204:205] op_sel_hi:[1,0]
	v_pk_mul_f32 v[68:69], v[66:67], v[204:205] op_sel_hi:[1,0]
	v_cvt_pk_bf16_f32 v66, v70, v71
	v_cvt_pk_bf16_f32 v67, v72, v73
	v_cvt_pk_bf16_f32 v68, v68, v69
	v_cvt_pk_bf16_f32 v69, v74, v75
	global_store_dwordx4 v[82:83], v[66:69], off offset:256
	s_nop 3
	s_waitcnt vmcnt(0)
; #define PG8_BAR __builtin_amdgcn_s_barrier()
;     __device__ __forceinline__ void operator()(const f32x4 (&acc)[2][2][4][2], const Unit& u, int wr, int wc, int fr, int fq) const {
;     ...
;             for (int m = 0; m < 4; ++m) {
;                 const int row = row0 + ai * HALF + m * 16; const float s = rs[row]; bf16_t* rowp = O + (size_t)row * ldc + col0;
; #pragma unroll
;                 for (int bj = 0; bj < 2; ++bj) { const f32x4 v0 = acc[ai][bj][m][0] * s, v1 = acc[ai][bj][m][1] * s; u32x4 w;
;                     w.x = pk2(v0[0], v0[1]); w.y = pk2(v0[2], v0[3]); w.z = pk2(v1[0], v1[1]); w.w = pk2(v1[2], v1[3]); *(u32x4*)(rowp + bj * HALF) = w; }
; template <class Epi, bool UPMODE>
; __device__ __forceinline__ void gemm_phase(LAS unsigned char* lds, const Gemm g, const StaticOrder& S, const Epi& E) {
;     ...
;         if (!has_next) break;
; #pragma unroll
;         for (int a = 0; a < 2; ++a)
; #pragma unroll
;             for (int b = 0; b < 2; ++b)
; #pragma unroll
;                 for (int m = 0; m < 4; ++m)
; #pragma unroll
;                     for (int n = 0; n < 2; ++n) acc[a][b][m][n] = (f32x4){0.f, 0.f, 0.f, 0.f};
;         cur = nxt; cA = nA; cB = nB; ++ui;
;         if (wr == 1) PG8_BAR;
	v_pk_mul_f32 v[62:63], v[62:63], v[232:233] op_sel_hi:[1,0]
	v_pk_mul_f32 v[64:65], v[64:65], v[232:233] op_sel_hi:[1,0]
	v_pk_mul_f32 v[70:71], v[60:61], v[232:233] op_sel_hi:[1,0]
	v_pk_mul_f32 v[60:61], v[58:59], v[232:233] op_sel_hi:[1,0]
	v_cvt_pk_bf16_f32 v58, v62, v63
	v_add_co_u32_e32 v62, vcc, s19, v140
	v_cvt_pk_bf16_f32 v59, v64, v65
	v_cvt_pk_bf16_f32 v60, v60, v61
	v_cvt_pk_bf16_f32 v61, v70, v71
	v_addc_co_u32_e32 v63, vcc, 0, v141, vcc
	global_store_dwordx4 v[62:63], v[58:61], off
	v_pk_mul_f32 v[56:57], v[56:57], v[232:233] op_sel_hi:[1,0]
	v_pk_mul_f32 v[54:55], v[54:55], v[232:233] op_sel_hi:[1,0]
	v_pk_mul_f32 v[58:59], v[52:53], v[232:233] op_sel_hi:[1,0]
	v_pk_mul_f32 v[52:53], v[50:51], v[232:233] op_sel_hi:[1,0]
	v_lshl_add_u64 v[68:69], v[140:141], 0, s[26:27]
	v_cvt_pk_bf16_f32 v50, v54, v55
	v_cvt_pk_bf16_f32 v51, v56, v57
	v_cvt_pk_bf16_f32 v52, v52, v53
	v_cvt_pk_bf16_f32 v53, v58, v59
	global_store_dwordx4 v[68:69], v[50:53], off offset:256
	s_nop 3
	s_mov_b32 s19, 0x90000
	s_mov_b64 s[26:27], 0x90000
	v_lshl_add_u64 v[52:53], v[140:141], 0, s[26:27]
	s_mov_b64 s[26:27], 0xa0000
	s_waitcnt vmcnt(0)
	v_pk_mul_f32 v[46:47], v[46:47], v[234:235] op_sel_hi:[1,0]
	v_pk_mul_f32 v[48:49], v[48:49], v[234:235] op_sel_hi:[1,0]
	v_pk_mul_f32 v[54:55], v[44:45], v[234:235] op_sel_hi:[1,0]
	v_pk_mul_f32 v[44:45], v[42:43], v[234:235] op_sel_hi:[1,0]
	v_cvt_pk_bf16_f32 v42, v46, v47
	v_add_co_u32_e32 v46, vcc, s19, v140
	v_cvt_pk_bf16_f32 v43, v48, v49
	v_cvt_pk_bf16_f32 v44, v44, v45
	v_cvt_pk_bf16_f32 v45, v54, v55
	v_addc_co_u32_e32 v47, vcc, 0, v141, vcc
	global_store_dwordx4 v[46:47], v[42:45], off
	v_pk_mul_f32 v[40:41], v[40:41], v[234:235] op_sel_hi:[1,0]
	v_pk_mul_f32 v[38:39], v[38:39], v[234:235] op_sel_hi:[1,0]
	v_pk_mul_f32 v[42:43], v[36:37], v[234:235] op_sel_hi:[1,0]
	v_pk_mul_f32 v[36:37], v[34:35], v[234:235] op_sel_hi:[1,0]
	v_cvt_pk_bf16_f32 v34, v38, v39
	v_cvt_pk_bf16_f32 v35, v40, v41
	v_cvt_pk_bf16_f32 v36, v36, v37
	v_cvt_pk_bf16_f32 v37, v42, v43
	global_store_dwordx4 v[52:53], v[34:37], off offset:256
	s_nop 3
	s_mov_b32 s19, 0xa0000
	v_lshl_add_u64 v[36:37], v[140:141], 0, s[26:27]
	s_mov_b64 s[26:27], 0xb0000
	s_waitcnt vmcnt(0)
	v_pk_mul_f32 v[30:31], v[30:31], v[236:237] op_sel_hi:[1,0]
	v_pk_mul_f32 v[32:33], v[32:33], v[236:237] op_sel_hi:[1,0]
	v_pk_mul_f32 v[38:39], v[28:29], v[236:237] op_sel_hi:[1,0]
	v_pk_mul_f32 v[28:29], v[26:27], v[236:237] op_sel_hi:[1,0]
	v_cvt_pk_bf16_f32 v26, v30, v31
	v_add_co_u32_e32 v30, vcc, s19, v140
	v_cvt_pk_bf16_f32 v27, v32, v33
	v_cvt_pk_bf16_f32 v28, v28, v29
	v_cvt_pk_bf16_f32 v29, v38, v39
	v_addc_co_u32_e32 v31, vcc, 0, v141, vcc
	global_store_dwordx4 v[30:31], v[26:29], off
	v_pk_mul_f32 v[24:25], v[24:25], v[236:237] op_sel_hi:[1,0]
	v_pk_mul_f32 v[22:23], v[22:23], v[236:237] op_sel_hi:[1,0]
	v_pk_mul_f32 v[26:27], v[20:21], v[236:237] op_sel_hi:[1,0]
	v_pk_mul_f32 v[20:21], v[18:19], v[236:237] op_sel_hi:[1,0]
	v_cvt_pk_bf16_f32 v18, v22, v23
	v_cvt_pk_bf16_f32 v19, v24, v25
	v_cvt_pk_bf16_f32 v20, v20, v21
	v_cvt_pk_bf16_f32 v21, v26, v27
	global_store_dwordx4 v[36:37], v[18:21], off offset:256
	s_nop 3
	s_mov_b32 s19, 0xb0000
	v_lshl_add_u64 v[20:21], v[140:141], 0, s[26:27]
	s_mov_b64 s[26:27], -1
	s_waitcnt vmcnt(0)
	v_pk_mul_f32 v[14:15], v[14:15], v[238:239] op_sel_hi:[1,0]
	v_pk_mul_f32 v[16:17], v[16:17], v[238:239] op_sel_hi:[1,0]
	v_pk_mul_f32 v[22:23], v[12:13], v[238:239] op_sel_hi:[1,0]
	v_pk_mul_f32 v[12:13], v[10:11], v[238:239] op_sel_hi:[1,0]
	v_cvt_pk_bf16_f32 v10, v14, v15
	v_add_co_u32_e32 v14, vcc, s19, v140
	v_cvt_pk_bf16_f32 v11, v16, v17
	v_cvt_pk_bf16_f32 v12, v12, v13
	v_cvt_pk_bf16_f32 v13, v22, v23
	v_addc_co_u32_e32 v15, vcc, 0, v141, vcc
	global_store_dwordx4 v[14:15], v[10:13], off
	v_pk_mul_f32 v[8:9], v[8:9], v[238:239] op_sel_hi:[1,0]
	v_pk_mul_f32 v[6:7], v[6:7], v[238:239] op_sel_hi:[1,0]
	v_pk_mul_f32 v[10:11], v[4:5], v[238:239] op_sel_hi:[1,0]
	v_pk_mul_f32 v[4:5], v[2:3], v[238:239] op_sel_hi:[1,0]
	v_cvt_pk_bf16_f32 v2, v6, v7
	v_cvt_pk_bf16_f32 v3, v8, v9
	v_cvt_pk_bf16_f32 v4, v4, v5
	v_cvt_pk_bf16_f32 v5, v10, v11
	s_andn2_b64 vcc, exec, s[6:7]
	global_store_dwordx4 v[20:21], v[2:5], off offset:256
	s_cbranch_vccnz .LBB0_154
	s_andn2_b64 vcc, exec, s[8:9]
	s_cbranch_vccnz .LBB0_153
	s_barrier
	s_branch .LBB0_153
